# K/V global prefetch issued right after the tile barrier (LDS write stays in PV0) in the GQA and differential-attention loops
# speedup vs baseline: 1.0063x; 1.0011x over previous
.Lfar_p1_main:
	s_waitcnt lgkmcnt(5)
	v_mfma_f32_32x32x16_bf16 v[96:111], v[178:181], v[112:115], v[80:95]
	ds_read_b128 v[178:181], v175 offset:4672
	s_waitcnt lgkmcnt(5)
	v_mfma_f32_32x32x16_bf16 v[96:111], v[206:209], v[116:119], v[96:111]
	ds_read_b128 v[206:209], v175 offset:4704
	s_waitcnt lgkmcnt(5)
	v_mfma_f32_32x32x16_bf16 v[96:111], v[210:213], v[120:123], v[96:111]
	ds_read_b128 v[210:213], v175 offset:17408
	s_waitcnt lgkmcnt(5)
	v_mfma_f32_32x32x16_bf16 v[96:111], v[214:217], v[124:127], v[96:111]
	ds_read_b128 v[214:217], v175 offset:22016
	s_waitcnt lgkmcnt(5)
	v_mfma_f32_32x32x16_bf16 v[80:95], v[230:233], v[112:115], v[80:95]
	ds_read_b128 v[230:233], v175 offset:26624
	s_waitcnt lgkmcnt(5)
	v_mfma_f32_32x32x16_bf16 v[80:95], v[236:239], v[116:119], v[80:95]
	ds_read_b128 v[236:239], v175 offset:31232
	v_add_u32_e32 v185, s26, v194
	v_add3_u32 v184, s26, v192, v193
	v_add_u32_e32 v218, v185, v197
	v_add_u32_e32 v185, v185, v196
	s_nop 0
	v_exp_f32_e32 v96, v96
	v_exp_f32_e32 v97, v97
	v_exp_f32_e32 v98, v98
	s_waitcnt lgkmcnt(5)
	v_mfma_f32_32x32x16_bf16 v[80:95], v[178:181], v[120:123], v[80:95]
	ds_read_b128 v[178:181], v175 offset:17440
	v_exp_f32_e32 v99, v99
	v_exp_f32_e32 v100, v100
	v_exp_f32_e32 v101, v101
	s_waitcnt lgkmcnt(5)
	v_mfma_f32_32x32x16_bf16 v[80:95], v[206:209], v[124:127], v[80:95]
	ds_read_b128 v[206:209], v175 offset:22048
	v_exp_f32_e32 v102, v102
	v_exp_f32_e32 v103, v103
	v_cvt_pk_bf16_f32 v96, v96, v97
	v_cvt_pk_bf16_f32 v97, v98, v99
	v_cvt_pk_bf16_f32 v98, v100, v101
	v_cvt_pk_bf16_f32 v99, v102, v103
	s_nop 1
	v_mfma_f32_16x16x32_bf16 v[248:251], v[226:229], v[96:99], v[248:251]
	v_exp_f32_e32 v104, v104
	v_exp_f32_e32 v105, v105
	v_exp_f32_e32 v106, v106
	s_waitcnt lgkmcnt(5)
	v_mfma_f32_32x32x16_bf16 v[48:63], v[210:213], v[96:99], v[48:63]
	ds_read_b128 v[210:213], v175 offset:26656
	s_waitcnt vmcnt(2)
	ds_write_b128 v184, v[128:131]
	v_exp_f32_e32 v107, v107
	v_exp_f32_e32 v108, v108
	v_exp_f32_e32 v109, v109
	s_waitcnt lgkmcnt(6)
	v_mfma_f32_32x32x16_bf16 v[32:47], v[214:217], v[96:99], v[32:47]
	ds_read_b128 v[214:217], v175 offset:31264
	s_waitcnt vmcnt(1)
	ds_write_b128 v185, v[132:135] offset:17408
	v_exp_f32_e32 v110, v110
	v_exp_f32_e32 v111, v111
	v_cvt_pk_bf16_f32 v104, v104, v105
	s_waitcnt lgkmcnt(7)
	v_mfma_f32_32x32x16_bf16 v[16:31], v[230:233], v[96:99], v[16:31]
	ds_read_b128 v[230:233], v175 offset:17472
	s_waitcnt vmcnt(0)
	ds_write_b128 v218, v[136:139] offset:17408
	v_cvt_pk_bf16_f32 v105, v106, v107
	v_cvt_pk_bf16_f32 v106, v108, v109
	v_cvt_pk_bf16_f32 v107, v110, v111
	s_waitcnt lgkmcnt(8)
	v_mfma_f32_32x32x16_bf16 v[0:15], v[236:239], v[96:99], v[0:15]
	ds_read_b128 v[236:239], v175 offset:22080
	v_mfma_f32_16x16x32_bf16 v[248:251], v[226:229], v[104:107], v[248:251]
	v_exp_f32_e32 v80, v80
	v_exp_f32_e32 v81, v81
	v_exp_f32_e32 v82, v82
	s_waitcnt lgkmcnt(8)
	v_mfma_f32_32x32x16_bf16 v[48:63], v[178:181], v[104:107], v[48:63]
	ds_read_b128 v[178:181], v175 offset:26688
	v_exp_f32_e32 v83, v83
	v_exp_f32_e32 v84, v84
	v_exp_f32_e32 v85, v85
	s_waitcnt lgkmcnt(8)
	v_mfma_f32_32x32x16_bf16 v[32:47], v[206:209], v[104:107], v[32:47]
	ds_read_b128 v[206:209], v175 offset:31296
	v_exp_f32_e32 v86, v86
	v_exp_f32_e32 v87, v87
	v_cvt_pk_bf16_f32 v80, v80, v81
	s_waitcnt lgkmcnt(8)
	v_mfma_f32_32x32x16_bf16 v[16:31], v[210:213], v[104:107], v[16:31]
	ds_read_b128 v[210:213], v175 offset:17504
	v_cvt_pk_bf16_f32 v81, v82, v83
	v_cvt_pk_bf16_f32 v82, v84, v85
	v_cvt_pk_bf16_f32 v83, v86, v87
	s_waitcnt lgkmcnt(7)
	v_mfma_f32_32x32x16_bf16 v[0:15], v[214:217], v[104:107], v[0:15]
	ds_read_b128 v[214:217], v175 offset:22112
	s_waitcnt lgkmcnt(5)
	s_barrier
	s_add_i32 s28, s12, 64
	s_cmpk_eq_i32 s28, 0x2000
	s_cbranch_scc1 .Lfar_p1_tailnp
	s_add_i32 s30, s21, s28
	s_addk_i32 s30, 0x99
	s_cmpk_gt_u32 s30, 0x112
	s_cbranch_scc0 .Lfar_p1_tailnp
	s_cmpk_gt_u32 s13, 0x7d
	s_cbranch_scc1 .Lfar_p1_noloada
	global_load_dwordx4 v[128:131], v[190:191], off
	global_load_dwordx4 v[132:135], v[188:189], off
	global_load_dwordx4 v[136:139], v[186:187], off
.Lfar_p1_noloada:
	v_mfma_f32_16x16x32_bf16 v[248:251], v[226:229], v[80:83], v[248:251]
	v_exp_f32_e32 v88, v88
	v_exp_f32_e32 v89, v89
	v_exp_f32_e32 v90, v90
	v_mfma_f32_32x32x16_bf16 v[48:63], v[230:233], v[80:83], v[48:63]
	ds_read_b128 v[230:233], v175 offset:26720
	v_exp_f32_e32 v91, v91
	v_exp_f32_e32 v92, v92
	v_exp_f32_e32 v93, v93
	s_waitcnt lgkmcnt(5)
	v_mfma_f32_32x32x16_bf16 v[32:47], v[236:239], v[80:83], v[32:47]
	ds_read_b128 v[236:239], v175 offset:31328
	v_exp_f32_e32 v94, v94
	v_exp_f32_e32 v95, v95
	v_cvt_pk_bf16_f32 v88, v88, v89
	s_waitcnt lgkmcnt(5)
	v_mfma_f32_32x32x16_bf16 v[16:31], v[178:181], v[80:83], v[16:31]
	v_add_u32_e32 v175, s26, v198
	ds_read_b128 v[178:181], v175
	v_cvt_pk_bf16_f32 v89, v90, v91
	v_cvt_pk_bf16_f32 v90, v92, v93
	v_cvt_pk_bf16_f32 v91, v94, v95
	s_waitcnt lgkmcnt(5)
	v_mfma_f32_32x32x16_bf16 v[0:15], v[206:209], v[80:83], v[0:15]
	ds_read_b128 v[206:209], v175 offset:32
	v_mfma_f32_16x16x32_bf16 v[248:251], v[226:229], v[88:91], v[248:251]
	s_add_i32 s12, s12, 64
	s_add_i32 s13, s13, 1
	s_waitcnt lgkmcnt(5)
	v_mfma_f32_32x32x16_bf16 v[48:63], v[210:213], v[88:91], v[48:63]
	ds_read_b128 v[210:213], v175 offset:64
	v_lshl_add_u64 v[186:187], v[186:187], 0, s[72:73]
	s_waitcnt lgkmcnt(5)
	v_mfma_f32_32x32x16_bf16 v[32:47], v[214:217], v[88:91], v[32:47]
	ds_read_b128 v[214:217], v175 offset:96
	v_lshl_add_u64 v[188:189], v[188:189], 0, s[72:73]
	s_waitcnt lgkmcnt(5)
	v_mfma_f32_32x32x16_bf16 v[16:31], v[230:233], v[88:91], v[16:31]
	ds_read_b128 v[230:233], v175 offset:4608
	v_lshl_add_u64 v[190:191], v[190:191], 0, s[0:1]
	s_mov_b32 s27, s26
	s_waitcnt lgkmcnt(5)
	v_mfma_f32_32x32x16_bf16 v[0:15], v[236:239], v[88:91], v[0:15]
	ds_read_b128 v[236:239], v175 offset:4640
	s_add_i32 s26, s27, 0x8c00
	s_cmp_lg_u32 s27, 0x11800
	s_cselect_b32 s26, s26, 0
	s_cmp_gt_i32 s30, -1
	s_cselect_b64 vcc, -1, 0
	s_nop 1
	v_cndmask_b32_e32 v80, v204, v205, vcc
	v_mov_b32_e32 v81, v80
	v_mov_b32_e32 v82, v80
	v_mov_b32_e32 v83, v80
	v_mov_b32_e32 v84, v80
	v_mov_b32_e32 v85, v80
	v_mov_b32_e32 v86, v80
	v_mov_b32_e32 v87, v80
	v_mov_b32_e32 v88, v80
	v_mov_b32_e32 v89, v80
	v_mov_b32_e32 v90, v80
	v_mov_b32_e32 v91, v80
	v_mov_b32_e32 v92, v80
	v_mov_b32_e32 v93, v80
	v_mov_b32_e32 v94, v80
	v_mov_b32_e32 v95, v80
	s_nop 0
	s_branch .Lfar_p1_main

.Lfar_p1_noloadb:
	v_mfma_f32_16x16x32_bf16 v[248:251], v[226:229], v[80:83], v[248:251]
	v_exp_f32_e32 v88, v88
	v_exp_f32_e32 v89, v89
	v_exp_f32_e32 v90, v90
	v_mfma_f32_32x32x16_bf16 v[48:63], v[230:233], v[80:83], v[48:63]
	ds_read_b128 v[230:233], v175 offset:26720
	v_exp_f32_e32 v91, v91
	v_exp_f32_e32 v92, v92
	v_exp_f32_e32 v93, v93
	s_waitcnt lgkmcnt(5)
	v_mfma_f32_32x32x16_bf16 v[32:47], v[236:239], v[80:83], v[32:47]
	ds_read_b128 v[236:239], v175 offset:31328
	v_exp_f32_e32 v94, v94
	v_exp_f32_e32 v95, v95
	v_cvt_pk_bf16_f32 v88, v88, v89
	s_waitcnt lgkmcnt(5)
	v_mfma_f32_32x32x16_bf16 v[16:31], v[178:181], v[80:83], v[16:31]
	v_cvt_pk_bf16_f32 v89, v90, v91
	v_cvt_pk_bf16_f32 v90, v92, v93
	v_cvt_pk_bf16_f32 v91, v94, v95
	s_waitcnt lgkmcnt(4)
	v_mfma_f32_32x32x16_bf16 v[0:15], v[206:209], v[80:83], v[0:15]
	v_mfma_f32_16x16x32_bf16 v[248:251], v[226:229], v[88:91], v[248:251]
	s_add_i32 s12, s12, 64
	s_add_i32 s13, s13, 1
	s_waitcnt lgkmcnt(3)
	v_mfma_f32_32x32x16_bf16 v[48:63], v[210:213], v[88:91], v[48:63]
	v_lshl_add_u64 v[186:187], v[186:187], 0, s[72:73]
	s_waitcnt lgkmcnt(2)
	v_mfma_f32_32x32x16_bf16 v[32:47], v[214:217], v[88:91], v[32:47]
	v_lshl_add_u64 v[188:189], v[188:189], 0, s[72:73]
	s_waitcnt lgkmcnt(1)
	v_mfma_f32_32x32x16_bf16 v[16:31], v[230:233], v[88:91], v[16:31]
	v_lshl_add_u64 v[190:191], v[190:191], 0, s[0:1]
	s_mov_b32 s27, s26
	s_waitcnt lgkmcnt(0)
	v_mfma_f32_32x32x16_bf16 v[0:15], v[236:239], v[88:91], v[0:15]
	s_cmpk_lg_i32 s12, 0x2000
	s_cbranch_scc0 .LBB0_1043
	s_branch .LBB0_1037

.Lfar_p2_main:
	s_waitcnt lgkmcnt(5)
	v_mfma_f32_32x32x16_bf16 v[96:111], v[178:181], v[112:115], v[80:95]
	ds_read_b128 v[178:181], v169 offset:4672
	s_waitcnt lgkmcnt(5)
	v_mfma_f32_32x32x16_bf16 v[96:111], v[206:209], v[116:119], v[96:111]
	ds_read_b128 v[206:209], v169 offset:4704
	s_waitcnt lgkmcnt(5)
	v_mfma_f32_32x32x16_bf16 v[96:111], v[210:213], v[120:123], v[96:111]
	ds_read_b128 v[210:213], v169 offset:17408
	s_waitcnt lgkmcnt(5)
	v_mfma_f32_32x32x16_bf16 v[96:111], v[214:217], v[124:127], v[96:111]
	ds_read_b128 v[214:217], v169 offset:22016
	s_waitcnt lgkmcnt(5)
	v_mfma_f32_32x32x16_bf16 v[80:95], v[230:233], v[112:115], v[80:95]
	ds_read_b128 v[230:233], v169 offset:26624
	s_waitcnt lgkmcnt(5)
	v_mfma_f32_32x32x16_bf16 v[80:95], v[236:239], v[116:119], v[80:95]
	ds_read_b128 v[236:239], v169 offset:31232
	v_add_u32_e32 v185, s12, v194
	v_add3_u32 v184, s12, v192, v193
	v_add_u32_e32 v218, v185, v197
	v_add_u32_e32 v185, v185, v196
	s_nop 0
	v_exp_f32_e32 v96, v96
	v_exp_f32_e32 v97, v97
	v_exp_f32_e32 v98, v98
	s_waitcnt lgkmcnt(5)
	v_mfma_f32_32x32x16_bf16 v[80:95], v[178:181], v[120:123], v[80:95]
	ds_read_b128 v[178:181], v169 offset:17440
	v_exp_f32_e32 v99, v99
	v_exp_f32_e32 v100, v100
	v_exp_f32_e32 v101, v101
	s_waitcnt lgkmcnt(5)
	v_mfma_f32_32x32x16_bf16 v[80:95], v[206:209], v[124:127], v[80:95]
	ds_read_b128 v[206:209], v169 offset:22048
	v_exp_f32_e32 v102, v102
	v_exp_f32_e32 v103, v103
	v_cvt_pk_bf16_f32 v96, v96, v97
	v_cvt_pk_bf16_f32 v97, v98, v99
	v_cvt_pk_bf16_f32 v98, v100, v101
	v_cvt_pk_bf16_f32 v99, v102, v103
	s_nop 1
	v_mfma_f32_16x16x32_bf16 v[248:251], v[226:229], v[96:99], v[248:251]
	v_exp_f32_e32 v104, v104
	v_exp_f32_e32 v105, v105
	v_exp_f32_e32 v106, v106
	s_waitcnt lgkmcnt(5)
	v_mfma_f32_32x32x16_bf16 v[48:63], v[210:213], v[96:99], v[48:63]
	ds_read_b128 v[210:213], v169 offset:26656
	s_waitcnt vmcnt(2)
	ds_write_b128 v184, v[128:131]
	v_exp_f32_e32 v107, v107
	v_exp_f32_e32 v108, v108
	v_exp_f32_e32 v109, v109
	s_waitcnt lgkmcnt(6)
	v_mfma_f32_32x32x16_bf16 v[32:47], v[214:217], v[96:99], v[32:47]
	ds_read_b128 v[214:217], v169 offset:31264
	s_waitcnt vmcnt(1)
	ds_write_b128 v185, v[132:135] offset:17408
	v_exp_f32_e32 v110, v110
	v_exp_f32_e32 v111, v111
	v_cvt_pk_bf16_f32 v104, v104, v105
	s_waitcnt lgkmcnt(7)
	v_mfma_f32_32x32x16_bf16 v[16:31], v[230:233], v[96:99], v[16:31]
	ds_read_b128 v[230:233], v169 offset:17472
	s_waitcnt vmcnt(0)
	ds_write_b128 v218, v[136:139] offset:17408
	v_cvt_pk_bf16_f32 v105, v106, v107
	v_cvt_pk_bf16_f32 v106, v108, v109
	v_cvt_pk_bf16_f32 v107, v110, v111
	s_waitcnt lgkmcnt(8)
	v_mfma_f32_32x32x16_bf16 v[0:15], v[236:239], v[96:99], v[0:15]
	ds_read_b128 v[236:239], v169 offset:22080
	v_mfma_f32_16x16x32_bf16 v[248:251], v[226:229], v[104:107], v[248:251]
	v_exp_f32_e32 v80, v80
	v_exp_f32_e32 v81, v81
	v_exp_f32_e32 v82, v82
	s_waitcnt lgkmcnt(8)
	v_mfma_f32_32x32x16_bf16 v[48:63], v[178:181], v[104:107], v[48:63]
	ds_read_b128 v[178:181], v169 offset:26688
	v_exp_f32_e32 v83, v83
	v_exp_f32_e32 v84, v84
	v_exp_f32_e32 v85, v85
	s_waitcnt lgkmcnt(8)
	v_mfma_f32_32x32x16_bf16 v[32:47], v[206:209], v[104:107], v[32:47]
	ds_read_b128 v[206:209], v169 offset:31296
	v_exp_f32_e32 v86, v86
	v_exp_f32_e32 v87, v87
	v_cvt_pk_bf16_f32 v80, v80, v81
	s_waitcnt lgkmcnt(8)
	v_mfma_f32_32x32x16_bf16 v[16:31], v[210:213], v[104:107], v[16:31]
	ds_read_b128 v[210:213], v169 offset:17504
	v_cvt_pk_bf16_f32 v81, v82, v83
	v_cvt_pk_bf16_f32 v82, v84, v85
	v_cvt_pk_bf16_f32 v83, v86, v87
	s_waitcnt lgkmcnt(7)
	v_mfma_f32_32x32x16_bf16 v[0:15], v[214:217], v[104:107], v[0:15]
	ds_read_b128 v[214:217], v169 offset:22112
	s_waitcnt lgkmcnt(5)
	s_barrier
	s_add_i32 s22, s10, 64
	s_cmpk_eq_i32 s22, 0x2000
	s_cbranch_scc1 .Lfar_p2_tailnp
	s_add_i32 s24, s21, s22
	s_addk_i32 s24, 0x99
	s_cmpk_gt_u32 s24, 0x112
	s_cbranch_scc0 .Lfar_p2_tailnp
	s_cmpk_gt_u32 s11, 0x7d
	s_cbranch_scc1 .Lfar_p2_noloada
	global_load_dwordx4 v[128:131], v[174:175], off
	global_load_dwordx4 v[132:135], v[172:173], off
	global_load_dwordx4 v[136:139], v[170:171], off
.Lfar_p2_noloada:
	v_mfma_f32_16x16x32_bf16 v[248:251], v[226:229], v[80:83], v[248:251]
	v_exp_f32_e32 v88, v88
	v_exp_f32_e32 v89, v89
	v_exp_f32_e32 v90, v90
	v_mfma_f32_32x32x16_bf16 v[48:63], v[230:233], v[80:83], v[48:63]
	ds_read_b128 v[230:233], v169 offset:26720
	v_exp_f32_e32 v91, v91
	v_exp_f32_e32 v92, v92
	v_exp_f32_e32 v93, v93
	s_waitcnt lgkmcnt(5)
	v_mfma_f32_32x32x16_bf16 v[32:47], v[236:239], v[80:83], v[32:47]
	ds_read_b128 v[236:239], v169 offset:31328
	v_exp_f32_e32 v94, v94
	v_exp_f32_e32 v95, v95
	v_cvt_pk_bf16_f32 v88, v88, v89
	s_waitcnt lgkmcnt(5)
	v_mfma_f32_32x32x16_bf16 v[16:31], v[178:181], v[80:83], v[16:31]
	v_add_u32_e32 v169, s12, v198
	ds_read_b128 v[178:181], v169
	v_cvt_pk_bf16_f32 v89, v90, v91
	v_cvt_pk_bf16_f32 v90, v92, v93
	v_cvt_pk_bf16_f32 v91, v94, v95
	s_waitcnt lgkmcnt(5)
	v_mfma_f32_32x32x16_bf16 v[0:15], v[206:209], v[80:83], v[0:15]
	ds_read_b128 v[206:209], v169 offset:32
	v_mfma_f32_16x16x32_bf16 v[248:251], v[226:229], v[88:91], v[248:251]
	s_add_i32 s10, s10, 64
	s_add_i32 s11, s11, 1
	s_waitcnt lgkmcnt(5)
	v_mfma_f32_32x32x16_bf16 v[48:63], v[210:213], v[88:91], v[48:63]
	ds_read_b128 v[210:213], v169 offset:64
	v_lshl_add_u64 v[170:171], v[170:171], 0, s[72:73]
	s_waitcnt lgkmcnt(5)
	v_mfma_f32_32x32x16_bf16 v[32:47], v[214:217], v[88:91], v[32:47]
	ds_read_b128 v[214:217], v169 offset:96
	v_lshl_add_u64 v[172:173], v[172:173], 0, s[72:73]
	s_waitcnt lgkmcnt(5)
	v_mfma_f32_32x32x16_bf16 v[16:31], v[230:233], v[88:91], v[16:31]
	ds_read_b128 v[230:233], v169 offset:4608
	v_lshl_add_u64 v[174:175], v[174:175], 0, s[0:1]
	s_mov_b32 s13, s12
	s_waitcnt lgkmcnt(5)
	v_mfma_f32_32x32x16_bf16 v[0:15], v[236:239], v[88:91], v[0:15]
	ds_read_b128 v[236:239], v169 offset:4640
	s_add_i32 s12, s13, 0x8c00
	s_cmp_lg_u32 s13, 0x11800
	s_cselect_b32 s12, s12, 0
	s_cmp_gt_i32 s24, -1
	s_cselect_b64 vcc, -1, 0
	s_nop 1
	v_cndmask_b32_e32 v80, v204, v205, vcc
	v_mov_b32_e32 v81, v80
	v_mov_b32_e32 v82, v80
	v_mov_b32_e32 v83, v80
	v_mov_b32_e32 v84, v80
	v_mov_b32_e32 v85, v80
	v_mov_b32_e32 v86, v80
	v_mov_b32_e32 v87, v80
	v_mov_b32_e32 v88, v80
	v_mov_b32_e32 v89, v80
	v_mov_b32_e32 v90, v80
	v_mov_b32_e32 v91, v80
	v_mov_b32_e32 v92, v80
	v_mov_b32_e32 v93, v80
	v_mov_b32_e32 v94, v80
	v_mov_b32_e32 v95, v80
	s_nop 0
	s_branch .Lfar_p2_main

.Lfar_p2_noloadb:
	v_mfma_f32_16x16x32_bf16 v[248:251], v[226:229], v[80:83], v[248:251]
	v_exp_f32_e32 v88, v88
	v_exp_f32_e32 v89, v89
	v_exp_f32_e32 v90, v90
	v_mfma_f32_32x32x16_bf16 v[48:63], v[230:233], v[80:83], v[48:63]
	ds_read_b128 v[230:233], v169 offset:26720
	v_exp_f32_e32 v91, v91
	v_exp_f32_e32 v92, v92
	v_exp_f32_e32 v93, v93
	s_waitcnt lgkmcnt(5)
	v_mfma_f32_32x32x16_bf16 v[32:47], v[236:239], v[80:83], v[32:47]
	ds_read_b128 v[236:239], v169 offset:31328
	v_exp_f32_e32 v94, v94
	v_exp_f32_e32 v95, v95
	v_cvt_pk_bf16_f32 v88, v88, v89
	s_waitcnt lgkmcnt(5)
	v_mfma_f32_32x32x16_bf16 v[16:31], v[178:181], v[80:83], v[16:31]
	v_cvt_pk_bf16_f32 v89, v90, v91
	v_cvt_pk_bf16_f32 v90, v92, v93
	v_cvt_pk_bf16_f32 v91, v94, v95
	s_waitcnt lgkmcnt(4)
	v_mfma_f32_32x32x16_bf16 v[0:15], v[206:209], v[80:83], v[0:15]
	v_mfma_f32_16x16x32_bf16 v[248:251], v[226:229], v[88:91], v[248:251]
	s_add_i32 s10, s10, 64
	s_add_i32 s11, s11, 1
	s_waitcnt lgkmcnt(3)
	v_mfma_f32_32x32x16_bf16 v[48:63], v[210:213], v[88:91], v[48:63]
	v_lshl_add_u64 v[170:171], v[170:171], 0, s[72:73]
	s_waitcnt lgkmcnt(2)
	v_mfma_f32_32x32x16_bf16 v[32:47], v[214:217], v[88:91], v[32:47]
	v_lshl_add_u64 v[172:173], v[172:173], 0, s[72:73]
	s_waitcnt lgkmcnt(1)
	v_mfma_f32_32x32x16_bf16 v[16:31], v[230:233], v[88:91], v[16:31]
	v_lshl_add_u64 v[174:175], v[174:175], 0, s[0:1]
	s_mov_b32 s13, s12
	s_waitcnt lgkmcnt(0)
	v_mfma_f32_32x32x16_bf16 v[0:15], v[236:239], v[88:91], v[0:15]
	s_cmpk_lg_i32 s10, 0x2000
	s_cbranch_scc0 .LBB0_1019
	s_branch .LBB0_1060

.Lgqa_main:
	v_mfma_f32_16x16x32_bf16 v[96:99], v[244:247], v[64:67], v[96:99]
	v_exp_f32_e32 v72, v72
	v_exp_f32_e32 v73, v73
	v_exp_f32_e32 v74, v74
	s_waitcnt lgkmcnt(3)
	v_mfma_f32_32x32x16_bf16 v[0:15], v[226:229], v[64:67], v[0:15]
	ds_read_b128 v[226:229], v248 offset:17472
	v_add3_u32 v249, s4, v193, v212
	v_add3_u32 v250, s4, v213, v214
	s_waitcnt vmcnt(1)
	ds_write_b128 v249, v[152:155]
	v_exp_f32_e32 v75, v75
	v_exp_f32_e32 v76, v76
	v_exp_f32_e32 v77, v77
	v_cvt_pk_bf16_f32 v72, v72, v73
	s_waitcnt lgkmcnt(4)
	v_mfma_f32_32x32x16_bf16 v[16:31], v[230:233], v[64:67], v[16:31]
	ds_read_b128 v[230:233], v248 offset:22080
	s_waitcnt vmcnt(0)
	ds_write_b128 v250, v[160:163] offset:17408
	v_exp_f32_e32 v78, v78
	v_exp_f32_e32 v79, v79
	v_cvt_pk_bf16_f32 v73, v74, v75
	v_cvt_pk_bf16_f32 v74, v76, v77
	v_cvt_pk_bf16_f32 v75, v78, v79
	s_nop 1
	v_mfma_f32_16x16x32_bf16 v[96:99], v[244:247], v[72:75], v[96:99]
	v_exp_f32_e32 v80, v80
	v_exp_f32_e32 v81, v81
	v_exp_f32_e32 v82, v82
	s_waitcnt lgkmcnt(5)
	v_mfma_f32_32x32x16_bf16 v[0:15], v[236:239], v[72:75], v[0:15]
	ds_read_b128 v[236:239], v248 offset:17504
	v_exp_f32_e32 v83, v83
	v_exp_f32_e32 v84, v84
	v_exp_f32_e32 v85, v85
	v_cvt_pk_bf16_f32 v80, v80, v81
	s_waitcnt lgkmcnt(5)
	v_mfma_f32_32x32x16_bf16 v[16:31], v[240:243], v[72:75], v[16:31]
	ds_read_b128 v[240:243], v248 offset:22112
	v_exp_f32_e32 v86, v86
	v_exp_f32_e32 v87, v87
	v_cvt_pk_bf16_f32 v81, v82, v83
	v_cvt_pk_bf16_f32 v82, v84, v85
	v_cvt_pk_bf16_f32 v83, v86, v87
	s_nop 1
	s_waitcnt lgkmcnt(2)
	s_barrier
	s_cmpk_eq_i32 s23, 0x7f
	s_cbranch_scc1 .Lgqa_last
	s_cmpk_gt_u32 s23, 0x7d
	s_cbranch_scc1 .Lgqa_noloada
	global_load_dwordx4 v[152:155], v[210:211], off
	global_load_dwordx4 v[160:163], v[208:209], off
.Lgqa_noloada:
	s_mov_b64 s[14:15], 0x60000
	s_mov_b64 s[16:17], 0x80
	v_mfma_f32_16x16x32_bf16 v[96:99], v[244:247], v[80:83], v[96:99]
	v_exp_f32_e32 v88, v88
	v_exp_f32_e32 v89, v89
	v_exp_f32_e32 v90, v90
	v_mfma_f32_32x32x16_bf16 v[0:15], v[226:229], v[80:83], v[0:15]
	v_add_u32_e32 v248, s4, v217
	ds_read_b128 v[226:229], v248
	v_exp_f32_e32 v91, v91
	v_exp_f32_e32 v92, v92
	v_exp_f32_e32 v93, v93
	v_cvt_pk_bf16_f32 v88, v88, v89
	v_mfma_f32_32x32x16_bf16 v[16:31], v[230:233], v[80:83], v[16:31]
	ds_read_b128 v[230:233], v248 offset:32
	v_exp_f32_e32 v94, v94
	v_exp_f32_e32 v95, v95
	v_cvt_pk_bf16_f32 v89, v90, v91
	v_cvt_pk_bf16_f32 v90, v92, v93
	v_cvt_pk_bf16_f32 v91, v94, v95
	s_nop 1
	v_mfma_f32_16x16x32_bf16 v[96:99], v[244:247], v[88:91], v[96:99]
	s_add_i32 s23, s23, 1
	v_lshl_add_u64 v[210:211], v[210:211], 0, s[14:15]
	s_waitcnt lgkmcnt(3)
	v_mfma_f32_32x32x16_bf16 v[0:15], v[236:239], v[88:91], v[0:15]
	ds_read_b128 v[236:239], v248 offset:64
	v_lshl_add_u64 v[208:209], v[208:209], 0, s[16:17]
	s_waitcnt lgkmcnt(3)
	v_mfma_f32_32x32x16_bf16 v[16:31], v[240:243], v[88:91], v[16:31]
	ds_read_b128 v[240:243], v248 offset:96
	s_mov_b32 s21, s4
	s_add_i32 s4, s21, 0x8c00
	s_cmp_lg_u32 s21, 0x11800
	s_cselect_b32 s4, s4, 0
	s_waitcnt lgkmcnt(3)
	v_mfma_f32_32x32x16_bf16 v[64:79], v[226:229], v[144:147], v[48:63]
	ds_read_b128 v[226:229], v248 offset:4608
	s_waitcnt lgkmcnt(3)
	v_mfma_f32_32x32x16_bf16 v[64:79], v[230:233], v[148:151], v[64:79]
	ds_read_b128 v[230:233], v248 offset:4640
	s_waitcnt lgkmcnt(3)
	v_mfma_f32_32x32x16_bf16 v[64:79], v[236:239], v[156:159], v[64:79]
	ds_read_b128 v[236:239], v248 offset:4672
	s_waitcnt lgkmcnt(3)
	v_mfma_f32_32x32x16_bf16 v[64:79], v[240:243], v[164:167], v[64:79]
	ds_read_b128 v[240:243], v248 offset:4704
	s_waitcnt lgkmcnt(3)
	v_mfma_f32_32x32x16_bf16 v[80:95], v[226:229], v[144:147], v[48:63]
	ds_read_b128 v[226:229], v248 offset:17408
	s_waitcnt lgkmcnt(3)
	v_mfma_f32_32x32x16_bf16 v[80:95], v[230:233], v[148:151], v[80:95]
	ds_read_b128 v[230:233], v248 offset:22016
	s_nop 4
	v_exp_f32_e32 v64, v64
	v_exp_f32_e32 v65, v65
	v_exp_f32_e32 v66, v66
	s_waitcnt lgkmcnt(3)
	v_mfma_f32_32x32x16_bf16 v[80:95], v[236:239], v[156:159], v[80:95]
	ds_read_b128 v[236:239], v248 offset:17440
	v_exp_f32_e32 v67, v67
	v_exp_f32_e32 v68, v68
	v_exp_f32_e32 v69, v69
	s_waitcnt lgkmcnt(3)
	v_mfma_f32_32x32x16_bf16 v[80:95], v[240:243], v[164:167], v[80:95]
	ds_read_b128 v[240:243], v248 offset:22048
	v_exp_f32_e32 v70, v70
	v_exp_f32_e32 v71, v71
	v_cvt_pk_bf16_f32 v64, v64, v65
	v_cvt_pk_bf16_f32 v65, v66, v67
	v_cvt_pk_bf16_f32 v66, v68, v69
	v_cvt_pk_bf16_f32 v67, v70, v71
	s_nop 1
	s_branch .Lgqa_main
